# P0 weight transposes: the 8 serialized ds_read2+wait per tile batched (issued together, counted lgkmcnt waits)
# baseline (speedup 1.0000x reference)
; __device__ __forceinline__ unsigned cvt_pk(float lo, float hi) { unsigned r; asm volatile("v_cvt_pk_bf16_f32 %0, %1, %2" : "=v"(r) : "v"(lo), "v"(hi)); return r; }
; template <int WID>
; __device__ __forceinline__ void transpose_tile(const Params& p, bf16_t* Wt, int K, int ldw, const float* W, int nt_, int kt_, LAS float* scr, int tid) {
;     ...
; #pragma unroll
;     for (int j = 0; j < 2; ++j) {
;         const int idx = tid + 512 * j; const int r = idx >> 4, kg = (idx & 15) * 8; u32x4 w;
;         w.x = cvt_pk(scr[(kg + 0) * 65 + r], scr[(kg + 1) * 65 + r]); w.y = cvt_pk(scr[(kg + 2) * 65 + r], scr[(kg + 3) * 65 + r]);
;         w.z = cvt_pk(scr[(kg + 4) * 65 + r], scr[(kg + 5) * 65 + r]); w.w = cvt_pk(scr[(kg + 6) * 65 + r], scr[(kg + 7) * 65 + r]);
;         *(u32x4*)(Wt + ((size_t)(n0 + r) * K + k0 + kg)) = w;
;     }
.LBB0_63:
	s_or_b64 exec, exec, s[4:5]
	s_waitcnt vmcnt(0)
	ds_write2_b32 v37, v6, v7 offset1:1
	ds_write2_b32 v37, v8, v9 offset0:2 offset1:3
	ds_write2_b32 v38, v2, v3 offset1:1
	ds_write2_b32 v39, v4, v5 offset1:1
	ds_write2_b32 v40, v14, v15 offset1:1
	ds_write2_b32 v41, v16, v17 offset1:1
	ds_write2_b32 v42, v10, v11 offset1:1
	ds_write2_b32 v43, v12, v13 offset1:1
	s_waitcnt lgkmcnt(0)
	s_barrier
	ds_read2_b32 v[100:101], v27 offset1:65
	ds_read2_b32 v[102:103], v27 offset0:130 offset1:195
	ds_read2_b32 v[104:105], v44 offset0:4 offset1:69
	ds_read2_b32 v[106:107], v44 offset0:134 offset1:199
	ds_read2_b32 v[108:109], v29 offset1:65
	ds_read2_b32 v[110:111], v29 offset0:130 offset1:195
	ds_read2_b32 v[112:113], v45 offset0:4 offset1:69
	ds_read2_b32 v[114:115], v45 offset0:134 offset1:199
	s_waitcnt lgkmcnt(7)
	v_cvt_pk_bf16_f32 v2, v100, v101
	s_waitcnt lgkmcnt(6)
	v_cvt_pk_bf16_f32 v3, v102, v103
	s_waitcnt lgkmcnt(5)
	v_cvt_pk_bf16_f32 v4, v104, v105
	s_add_i32 s46, s46, s6
	s_waitcnt lgkmcnt(4)
	v_cvt_pk_bf16_f32 v5, v106, v107
	v_add_u32_e32 v6, s46, v25
	s_ashr_i32 s1, s0, 31
	v_ashrrev_i32_e32 v7, 31, v6
	v_lshl_add_u64 v[8:9], s[0:1], 1, v[20:21]
	v_lshlrev_b64 v[6:7], 12, v[6:7]
	v_lshl_add_u64 v[6:7], v[8:9], 0, v[6:7]
	global_store_dwordx4 v[6:7], v[2:5], off
	s_waitcnt lgkmcnt(3)
	s_nop 0
	v_cvt_pk_bf16_f32 v2, v108, v109
	v_add_u32_e32 v10, s46, v28
	v_ashrrev_i32_e32 v11, 31, v10
	v_lshlrev_b64 v[10:11], 12, v[10:11]
	s_waitcnt lgkmcnt(2)
	v_cvt_pk_bf16_f32 v3, v110, v111
	v_lshl_add_u64 v[8:9], v[8:9], 0, v[10:11]
	s_waitcnt lgkmcnt(1)
	v_cvt_pk_bf16_f32 v4, v112, v113
	s_waitcnt lgkmcnt(0)
	v_cvt_pk_bf16_f32 v5, v114, v115
	global_store_dwordx4 v[8:9], v[2:5], off
	s_barrier

; template <int WID>
; __device__ __forceinline__ void transpose_tile(const Params& p, bf16_t* Wt, int K, int ldw, const float* W, int nt_, int kt_, LAS float* scr, int tid) {
;     const int n0 = nt_ * 64, k0 = kt_ * 128;
;     {
;         const int c4 = (tid & 15) * 4; const int np = n0 + c4; int sc;
;         if (WID == 0) { sc = np < 1792 ? np : (np < 1856 ? 1792 + sigma64(np - 1792) : -1); }
;         else if (WID == 2) { const int h = np / 192, d = np - h * 192; sc = d < 128 ? np : h * 192 + 128 + sigma64(d - 128); }
;         else if (WID == 5) { const int i32 = np & 31; const int jj = (np & 96) + 8 * ((i32 >> 2) & 3) + 4 * (i32 >> 4) + (i32 & 3); sc = ((np >> 7) & 1) * DFF + (np >> 8) * 128 + jj; }
;         else sc = np;
;         f32x4 v[4];
; #pragma unroll
;         for (int i = 0; i < 4; ++i) { const int kk = (tid >> 4) + 32 * i; v[i] = sc >= 0 ? __builtin_nontemporal_load((const f32x4*)(W + (size_t)(k0 + kk) * ldw + sc)) : (f32x4){0.f, 0.f, 0.f, 0.f}; }
; #pragma unroll
;         for (int i = 0; i < 4; ++i) {
;             const int kk = (tid >> 4) + 32 * i; const int k = k0 + kk; float ksc = 1.0f;
;             if (WID == 2) ksc = p.in[14][k];
;             if (WID == 3) ksc = p.in[16][k];
;             if (WID == 4) ksc = (k < 1024 ? p.in[18][k] : p.in[19][k - 1024]);
;             if (WID == 5) ksc = p.in[21][k];
; #pragma unroll
; __global__ void __launch_bounds__(NTHR, 2) fwd_megakernel(Params p) {
;     ...
;         for (int it = bid; it < T6; it += G) {
;             if (it < T0) { transpose_tile<0>(p, WinT, 2048, 1856, p.in[3], it % 32, it / 32, scr, tid); }
;             else if (it < T1) { const int j = it - T0; transpose_tile<1>(p, WgluT, 1024, 1024, p.in[12], j % 16, j / 16, scr, tid); }
;             else if (it < T2) { const int j = it - T1; transpose_tile<2>(p, WqT, 512, 1536, p.in[15], j % 24, j / 24, scr, tid); }
;             else if (it < T3) { const int j = it - T2; transpose_tile<3>(p, WkvT, 256, 2048, p.in[17], j % 32, j / 32, scr, tid); }
;             else if (it < T4) { const int j = it - T3; transpose_tile<4>(p, WoutT, 2048, 2048, p.in[20], j % 32, j / 32, scr, tid); }
;             else if (it < T5) { const int j = it - T4; transpose_tile<5>(p, WupT, 2048, 2 * DFF, p.in[22], j % 172, j / 172, scr, tid); }
;             else { const int j = it - T5; transpose_tile<6>(p, WdT, DFF, 2048, p.in[25], j % 32, j / 32, scr, tid); }
.LBB0_65:
	s_cmpk_gt_i32 s45, 0x1ff
	s_mov_b64 s[0:1], -1
	s_cbranch_scc0 .LBB0_89
	s_cmpk_gt_u32 s45, 0x27f
	s_cbranch_scc0 .LBB0_86
	s_cmpk_gt_u32 s45, 0x2df
	s_cbranch_scc0 .LBB0_81
	s_cmpk_gt_u32 s45, 0x31f
	s_cbranch_scc0 .LBB0_78
	s_cmpk_gt_u32 s45, 0x51f
	s_cbranch_scc0 .LBB0_75
	s_cmpk_gt_u32 s45, 0xfdf
	s_cbranch_scc0 .LBB0_72
	s_and_b32 s0, s6, 0x7c0
	s_and_b32 s1, s9, 0x7fffff80
	s_addk_i32 s1, 0xc080
	v_or_b32_e32 v2, s0, v1
	v_readlane_b32 s16, v241, 0
	v_or_b32_e32 v4, s1, v25
	v_lshlrev_b32_e32 v18, 2, v2
	v_readlane_b32 s18, v241, 2
	v_readlane_b32 s19, v241, 3
	v_readlane_b32 s17, v241, 1
	v_readlane_b32 s20, v241, 4
	v_lshl_add_u64 v[2:3], s[18:19], 0, v[18:19]
	v_lshlrev_b32_e32 v18, 11, v4
	v_lshl_add_u64 v[14:15], v[18:19], 2, v[2:3]
	v_add_co_u32_e32 v6, vcc, 0x40000, v14
	v_readlane_b32 s21, v241, 5
	s_nop 0
	v_addc_co_u32_e32 v7, vcc, 0, v15, vcc
	global_load_dwordx4 v[2:5], v[14:15], off nt
	s_nop 0
	global_load_dwordx4 v[6:9], v[6:7], off nt
	v_add_co_u32_e32 v10, vcc, 0x80000, v14
	v_readlane_b32 s22, v241, 6
	s_nop 0
	v_addc_co_u32_e32 v11, vcc, 0, v15, vcc
	global_load_dwordx4 v[10:13], v[10:11], off nt
	v_add_co_u32_e32 v14, vcc, 0xc0000, v14
	v_readlane_b32 s23, v241, 7
	s_nop 0
	v_addc_co_u32_e32 v15, vcc, 0, v15, vcc
	global_load_dwordx4 v[14:17], v[14:15], off nt
	s_waitcnt vmcnt(3)
	ds_write2_b32 v37, v2, v3 offset1:1
	ds_write2_b32 v37, v4, v5 offset0:2 offset1:3
	s_waitcnt vmcnt(2)
	ds_write2_b32 v38, v6, v7 offset1:1
	ds_write2_b32 v39, v8, v9 offset1:1
	s_waitcnt vmcnt(1)
	ds_write2_b32 v40, v10, v11 offset1:1
	ds_write2_b32 v41, v12, v13 offset1:1
	s_waitcnt vmcnt(0)
	ds_write2_b32 v42, v14, v15 offset1:1
	ds_write2_b32 v43, v16, v17 offset1:1
	s_waitcnt lgkmcnt(0)
	s_barrier
	ds_read2_b32 v[100:101], v27 offset1:65
	ds_read2_b32 v[102:103], v27 offset0:130 offset1:195
	ds_read2_b32 v[104:105], v44 offset0:4 offset1:69
	ds_read2_b32 v[106:107], v44 offset0:134 offset1:199
	ds_read2_b32 v[108:109], v29 offset1:65
	ds_read2_b32 v[110:111], v29 offset0:130 offset1:195
	ds_read2_b32 v[112:113], v45 offset0:4 offset1:69
	ds_read2_b32 v[114:115], v45 offset0:134 offset1:199
	s_waitcnt lgkmcnt(7)
	v_cvt_pk_bf16_f32 v2, v100, v101
	v_or_b32_e32 v8, s0, v25
	v_or_b32_e32 v10, s1, v26
	s_waitcnt lgkmcnt(6)
	v_cvt_pk_bf16_f32 v3, v102, v103
	v_mad_u32_u24 v18, v8, s15, v10
	s_waitcnt lgkmcnt(5)
	v_cvt_pk_bf16_f32 v4, v104, v105
	s_waitcnt lgkmcnt(4)
	v_cvt_pk_bf16_f32 v5, v106, v107
	v_lshl_add_u64 v[8:9], v[18:19], 1, s[50:51]
	global_store_dwordx4 v[8:9], v[2:5], off
	s_waitcnt lgkmcnt(3)
	s_nop 0
	v_cvt_pk_bf16_f32 v2, v108, v109
	s_waitcnt lgkmcnt(2)
	v_cvt_pk_bf16_f32 v3, v110, v111
	s_waitcnt lgkmcnt(1)
	v_cvt_pk_bf16_f32 v4, v112, v113
	v_add_u32_e32 v5, s0, v28
	v_mad_u32_u24 v18, v5, s15, v10
	v_lshl_add_u64 v[8:9], v[18:19], 1, s[50:51]
	s_waitcnt lgkmcnt(0)
	v_cvt_pk_bf16_f32 v5, v114, v115
	global_store_dwordx4 v[8:9], v[2:5], off
	s_barrier
	s_mov_b64 s[0:1], 0
; __device__ __forceinline__ unsigned cvt_pk(float lo, float hi) { unsigned r; asm volatile("v_cvt_pk_bf16_f32 %0, %1, %2" : "=v"(r) : "v"(lo), "v"(hi)); return r; }
; __device__ __forceinline__ int sigma64(int p) { return (p >> 5) * 16 + (p & 15) + 32 * ((p >> 4) & 1); }
; template <int WID>
; __device__ __forceinline__ void transpose_tile(const Params& p, bf16_t* Wt, int K, int ldw, const float* W, int nt_, int kt_, LAS float* scr, int tid) {
;     ...
;     {
;         const int c4 = (tid & 15) * 4; const int np = n0 + c4; int sc;
;         if (WID == 0) { sc = np < 1792 ? np : (np < 1856 ? 1792 + sigma64(np - 1792) : -1); }
;         else if (WID == 2) { const int h = np / 192, d = np - h * 192; sc = d < 128 ? np : h * 192 + 128 + sigma64(d - 128); }
;         else if (WID == 5) { const int i32 = np & 31; const int jj = (np & 96) + 8 * ((i32 >> 2) & 3) + 4 * (i32 >> 4) + (i32 & 3); sc = ((np >> 7) & 1) * DFF + (np >> 8) * 128 + jj; }
;         else sc = np;
;         f32x4 v[4];
; #pragma unroll
;         for (int i = 0; i < 4; ++i) { const int kk = (tid >> 4) + 32 * i; v[i] = sc >= 0 ? __builtin_nontemporal_load((const f32x4*)(W + (size_t)(k0 + kk) * ldw + sc)) : (f32x4){0.f, 0.f, 0.f, 0.f}; }
; #pragma unroll
;         for (int i = 0; i < 4; ++i) {
;             const int kk = (tid >> 4) + 32 * i; const int k = k0 + kk; float ksc = 1.0f;
;             if (WID == 2) ksc = p.in[14][k];
;             if (WID == 3) ksc = p.in[16][k];
;             if (WID == 4) ksc = (k < 1024 ? p.in[18][k] : p.in[19][k - 1024]);
;             if (WID == 5) ksc = p.in[21][k];
; #pragma unroll
;             for (int e = 0; e < 4; ++e) scr[kk * 65 + c4 + e] = v[i][e] * ksc;
;         }
;     }
;     __syncthreads();
; #pragma unroll
;     for (int j = 0; j < 2; ++j) {
;         const int idx = tid + 512 * j; const int r = idx >> 4, kg = (idx & 15) * 8; u32x4 w;
;         w.x = cvt_pk(scr[(kg + 0) * 65 + r], scr[(kg + 1) * 65 + r]); w.y = cvt_pk(scr[(kg + 2) * 65 + r], scr[(kg + 3) * 65 + r]);
;         w.z = cvt_pk(scr[(kg + 4) * 65 + r], scr[(kg + 5) * 65 + r]); w.w = cvt_pk(scr[(kg + 6) * 65 + r], scr[(kg + 7) * 65 + r]);
;         *(u32x4*)(Wt + ((size_t)(n0 + r) * K + k0 + kg)) = w;
;     }
;     __syncthreads();
.LBB0_72:
	s_andn2_b64 vcc, exec, s[0:1]
	s_cbranch_vccnz .LBB0_74
	s_add_i32 s0, s45, 0xfae0
	s_and_b32 s1, s0, 0xffff
	s_mul_i32 s1, s1, 0xbe83
	s_lshr_b32 s4, s1, 16
	s_lshr_b32 s1, s1, 23
	s_mulk_i32 s1, 0xac
	s_sub_i32 s0, s0, s1
	s_and_b32 s1, s0, 0xffff
	s_lshl_b32 s5, s1, 6
	s_bfe_i32 s0, s0, 0x10001
	s_lshl_b32 s1, s1, 5
	s_and_b32 s0, s0, 0x1580
	s_and_b32 s1, s1, 0x1f80
	s_and_b32 s4, s4, 0xff80
	v_bitop3_b32 v2, s5, v46, v1 bitop3:0xc8
	s_add_i32 s0, s0, s1
	v_or3_b32 v2, s0, v30, v2
	v_or_b32_e32 v16, s4, v25
	v_readlane_b32 s68, v241, 24
	v_lshlrev_b32_e32 v18, 2, v2
	v_readlane_b32 s80, v241, 36
	v_readlane_b32 s81, v241, 37
	v_mul_u32_u24_e32 v4, 0x2b00, v16
	s_mov_b32 s0, 0x158000
	v_lshl_add_u64 v[2:3], s[80:81], 0, v[18:19]
	v_lshlrev_b32_e32 v18, 2, v4
	v_lshl_add_u64 v[14:15], v[2:3], 0, v[18:19]
	v_add_co_u32_e32 v6, vcc, s0, v14
	s_mov_b32 s0, 0x2b0000
	s_nop 0
	v_addc_co_u32_e32 v7, vcc, 0, v15, vcc
	v_add_co_u32_e32 v10, vcc, s0, v14
	s_mov_b32 s0, 0x408000
	s_nop 0
	v_addc_co_u32_e32 v11, vcc, 0, v15, vcc
	v_readlane_b32 s78, v241, 34
	v_readlane_b32 s79, v241, 35
	global_load_dwordx4 v[2:5], v[14:15], off nt
	s_nop 0
	global_load_dwordx4 v[6:9], v[6:7], off nt
	v_lshlrev_b32_e32 v16, 2, v16
	v_add_co_u32_e32 v14, vcc, s0, v14
	global_load_dwordx4 v[10:13], v[10:11], off nt
	s_nop 0
	global_load_dword v18, v16, s[78:79]
	global_load_dword v22, v16, s[78:79] offset:128
	v_addc_co_u32_e32 v15, vcc, 0, v15, vcc
	global_load_dword v48, v16, s[78:79] offset:256
	global_load_dword v50, v16, s[78:79] offset:384
	v_readlane_b32 s0, v241, 42
	global_load_dwordx4 v[14:17], v[14:15], off nt
	v_readlane_b32 s1, v241, 43
	v_readlane_b32 s69, v241, 25
	v_readlane_b32 s70, v241, 26
	v_readlane_b32 s71, v241, 27
	v_readlane_b32 s72, v241, 28
	v_readlane_b32 s73, v241, 29
	v_readlane_b32 s74, v241, 30
	v_readlane_b32 s75, v241, 31
	v_readlane_b32 s76, v241, 32
	v_readlane_b32 s77, v241, 33
	v_readlane_b32 s82, v241, 38
	v_readlane_b32 s83, v241, 39
	v_readlane_b32 s68, v241, 44
	v_readlane_b32 s54, v241, 60
	v_readlane_b32 s70, v241, 46
	v_readlane_b32 s71, v241, 47
	v_readlane_b32 s72, v241, 48
	v_readlane_b32 s73, v241, 49
	v_readlane_b32 s74, v241, 50
	v_readlane_b32 s75, v241, 51
	v_readlane_b32 s82, v241, 58
	v_readlane_b32 s83, v241, 59
	v_readlane_b32 s55, v241, 61
	v_readlane_b32 s69, v241, 45
	v_readlane_b32 s76, v241, 52
	v_readlane_b32 s77, v241, 53
	v_readlane_b32 s78, v241, 54
	v_readlane_b32 s79, v241, 55
	v_readlane_b32 s80, v241, 56
	v_readlane_b32 s81, v241, 57
	s_waitcnt vmcnt(4)
	v_pk_mul_f32 v[2:3], v[2:3], v[18:19] op_sel_hi:[1,0]
	v_pk_mul_f32 v[4:5], v[4:5], v[18:19] op_sel_hi:[1,0]
	ds_write2_b32 v37, v2, v3 offset1:1
	ds_write2_b32 v37, v4, v5 offset0:2 offset1:3
	s_waitcnt vmcnt(3)
	v_pk_mul_f32 v[2:3], v[6:7], v[22:23] op_sel_hi:[1,0]
	v_pk_mul_f32 v[4:5], v[8:9], v[22:23] op_sel_hi:[1,0]
	s_waitcnt vmcnt(2)
	v_pk_mul_f32 v[6:7], v[10:11], v[48:49] op_sel_hi:[1,0]
	v_pk_mul_f32 v[8:9], v[12:13], v[48:49] op_sel_hi:[1,0]
	s_waitcnt vmcnt(0)
	v_pk_mul_f32 v[10:11], v[14:15], v[50:51] op_sel_hi:[1,0]
	v_pk_mul_f32 v[12:13], v[16:17], v[50:51] op_sel_hi:[1,0]
	ds_write2_b32 v38, v2, v3 offset1:1
	ds_write2_b32 v39, v4, v5 offset1:1
	ds_write2_b32 v40, v6, v7 offset1:1
	ds_write2_b32 v41, v8, v9 offset1:1
	ds_write2_b32 v42, v10, v11 offset1:1
	ds_write2_b32 v43, v12, v13 offset1:1
	s_waitcnt lgkmcnt(0)
	s_barrier
	ds_read2_b32 v[100:101], v27 offset1:65
	ds_read2_b32 v[102:103], v27 offset0:130 offset1:195
	ds_read2_b32 v[104:105], v44 offset0:4 offset1:69
	ds_read2_b32 v[106:107], v44 offset0:134 offset1:199
	ds_read2_b32 v[108:109], v29 offset1:65
	ds_read2_b32 v[110:111], v29 offset0:130 offset1:195
	ds_read2_b32 v[112:113], v45 offset0:4 offset1:69
	ds_read2_b32 v[114:115], v45 offset0:134 offset1:199
	s_waitcnt lgkmcnt(7)
	v_cvt_pk_bf16_f32 v2, v100, v101
	v_or_b32_e32 v8, s5, v25
	s_waitcnt lgkmcnt(6)
	v_cvt_pk_bf16_f32 v3, v102, v103
	v_lshl_or_b32 v8, v8, 11, v26
	s_waitcnt lgkmcnt(5)
	v_cvt_pk_bf16_f32 v4, v104, v105
	s_waitcnt lgkmcnt(4)
	v_cvt_pk_bf16_f32 v5, v106, v107
	v_add_lshl_u32 v8, v8, s4, 1
	global_store_dwordx4 v8, v[2:5], s[0:1]
	s_waitcnt lgkmcnt(3)
	s_nop 0
	v_cvt_pk_bf16_f32 v2, v108, v109
	s_waitcnt lgkmcnt(2)
	v_cvt_pk_bf16_f32 v3, v110, v111
	s_waitcnt lgkmcnt(1)
	v_cvt_pk_bf16_f32 v4, v112, v113
	v_add_u32_e32 v5, s5, v28
	v_lshl_or_b32 v5, v5, 11, v26
	v_add_lshl_u32 v8, v5, s4, 1
	s_waitcnt lgkmcnt(0)
	v_cvt_pk_bf16_f32 v5, v114, v115
	global_store_dwordx4 v8, v[2:5], s[0:1]
	s_barrier

; __device__ __forceinline__ unsigned cvt_pk(float lo, float hi) { unsigned r; asm volatile("v_cvt_pk_bf16_f32 %0, %1, %2" : "=v"(r) : "v"(lo), "v"(hi)); return r; }
; __device__ __forceinline__ int sigma64(int p) { return (p >> 5) * 16 + (p & 15) + 32 * ((p >> 4) & 1); }
; template <int WID>
; __device__ __forceinline__ void transpose_tile(const Params& p, bf16_t* Wt, int K, int ldw, const float* W, int nt_, int kt_, LAS float* scr, int tid) {
;     ...
;     {
;         const int c4 = (tid & 15) * 4; const int np = n0 + c4; int sc;
;         if (WID == 0) { sc = np < 1792 ? np : (np < 1856 ? 1792 + sigma64(np - 1792) : -1); }
;         else if (WID == 2) { const int h = np / 192, d = np - h * 192; sc = d < 128 ? np : h * 192 + 128 + sigma64(d - 128); }
;         else if (WID == 5) { const int i32 = np & 31; const int jj = (np & 96) + 8 * ((i32 >> 2) & 3) + 4 * (i32 >> 4) + (i32 & 3); sc = ((np >> 7) & 1) * DFF + (np >> 8) * 128 + jj; }
;         else sc = np;
;         f32x4 v[4];
; #pragma unroll
;         for (int i = 0; i < 4; ++i) { const int kk = (tid >> 4) + 32 * i; v[i] = sc >= 0 ? __builtin_nontemporal_load((const f32x4*)(W + (size_t)(k0 + kk) * ldw + sc)) : (f32x4){0.f, 0.f, 0.f, 0.f}; }
; #pragma unroll
;         for (int i = 0; i < 4; ++i) {
;             const int kk = (tid >> 4) + 32 * i; const int k = k0 + kk; float ksc = 1.0f;
;             if (WID == 2) ksc = p.in[14][k];
;             if (WID == 3) ksc = p.in[16][k];
;             if (WID == 4) ksc = (k < 1024 ? p.in[18][k] : p.in[19][k - 1024]);
;             if (WID == 5) ksc = p.in[21][k];
; #pragma unroll
;             for (int e = 0; e < 4; ++e) scr[kk * 65 + c4 + e] = v[i][e] * ksc;
;         }
;     }
;     __syncthreads();
; #pragma unroll
;     for (int j = 0; j < 2; ++j) {
;         const int idx = tid + 512 * j; const int r = idx >> 4, kg = (idx & 15) * 8; u32x4 w;
;         w.x = cvt_pk(scr[(kg + 0) * 65 + r], scr[(kg + 1) * 65 + r]); w.y = cvt_pk(scr[(kg + 2) * 65 + r], scr[(kg + 3) * 65 + r]);
;         w.z = cvt_pk(scr[(kg + 4) * 65 + r], scr[(kg + 5) * 65 + r]); w.w = cvt_pk(scr[(kg + 6) * 65 + r], scr[(kg + 7) * 65 + r]);
;         *(u32x4*)(Wt + ((size_t)(n0 + r) * K + k0 + kg)) = w;
;     }
;     __syncthreads();
.LBB0_75:
	s_andn2_b64 vcc, exec, s[0:1]
	s_cbranch_vccnz .LBB0_77
	s_and_b32 s4, s6, 0x7c0
	s_add_i32 s1, s9, 0xfffff380
	s_and_b32 s5, s1, 0x7fffff80
	v_or_b32_e32 v2, s4, v1
	v_readlane_b32 s68, v241, 24
	v_or_b32_e32 v14, s5, v25
	v_lshlrev_b32_e32 v18, 2, v2
	v_readlane_b32 s76, v241, 32
	v_readlane_b32 s77, v241, 33
	s_add_i32 s0, s45, 0xfffffce0
	v_mov_b32_e32 v15, v19
	v_lshl_add_u64 v[2:3], s[76:77], 0, v[18:19]
	v_lshlrev_b32_e32 v18, 11, v14
	v_lshl_add_u64 v[16:17], v[18:19], 2, v[2:3]
	v_add_co_u32_e32 v6, vcc, 0x40000, v16
	v_readlane_b32 s72, v241, 28
	s_nop 0
	v_addc_co_u32_e32 v7, vcc, 0, v17, vcc
	v_add_co_u32_e32 v10, vcc, 0x80000, v16
	v_readlane_b32 s73, v241, 29
	s_nop 0
	v_addc_co_u32_e32 v11, vcc, 0, v17, vcc
	v_readlane_b32 s74, v241, 30
	v_readlane_b32 s75, v241, 31
	global_load_dwordx4 v[2:5], v[16:17], off nt
	s_nop 0
	global_load_dwordx4 v[6:9], v[6:7], off nt
	v_add_co_u32_e32 v16, vcc, 0xc0000, v16
	s_cmpk_lt_u32 s0, 0x100
	v_lshlrev_b64 v[14:15], 2, v[14:15]
	s_movk_i32 s0, 0xf000
	v_addc_co_u32_e32 v17, vcc, 0, v17, vcc
	v_lshl_add_u64 v[22:23], s[72:73], 0, v[14:15]
	v_lshl_add_u64 v[14:15], s[74:75], 0, v[14:15]
	s_mov_b32 s1, -1
	v_lshl_add_u64 v[48:49], v[14:15], 0, s[0:1]
	s_cselect_b64 vcc, -1, 0
	v_cndmask_b32_e32 v49, v49, v23, vcc
	v_cndmask_b32_e32 v48, v48, v22, vcc
	s_mov_b64 s[0:1], 0x80
	global_load_dword v18, v[48:49], off
	v_lshl_add_u64 v[48:49], v[22:23], 0, s[0:1]
	s_movk_i32 s0, 0xf080
	s_mov_b32 s1, -1
	v_lshl_add_u64 v[50:51], v[14:15], 0, s[0:1]
	s_mov_b64 s[0:1], 0x100
	v_cndmask_b32_e32 v49, v51, v49, vcc
	v_cndmask_b32_e32 v48, v50, v48, vcc
	v_lshl_add_u64 v[50:51], v[22:23], 0, s[0:1]
	s_movk_i32 s0, 0xf100
	s_mov_b32 s1, -1
	v_lshl_add_u64 v[52:53], v[14:15], 0, s[0:1]
	s_mov_b64 s[0:1], 0x180
	v_lshl_add_u64 v[22:23], v[22:23], 0, s[0:1]
	s_movk_i32 s0, 0xf180
	s_mov_b32 s1, -1
	v_cndmask_b32_e32 v51, v53, v51, vcc
	v_cndmask_b32_e32 v50, v52, v50, vcc
	v_lshl_add_u64 v[14:15], v[14:15], 0, s[0:1]
	v_cmp_lt_u32_e32 vcc, s5, v33
	global_load_dwordx4 v[10:13], v[10:11], off nt
	v_readlane_b32 s69, v241, 25
	global_load_dword v48, v[48:49], off
	v_cndmask_b32_e32 v15, v15, v23, vcc
	global_load_dword v50, v[50:51], off
	v_cndmask_b32_e32 v14, v14, v22, vcc
	global_load_dword v22, v[14:15], off
	s_nop 0
	global_load_dwordx4 v[14:17], v[16:17], off nt
	v_readlane_b32 s70, v241, 26
	v_readlane_b32 s71, v241, 27
	v_readlane_b32 s78, v241, 34
	v_readlane_b32 s79, v241, 35
	v_readlane_b32 s80, v241, 36
	v_readlane_b32 s81, v241, 37
	v_readlane_b32 s82, v241, 38
	v_readlane_b32 s83, v241, 39
	v_readlane_b32 s68, v241, 44
	v_readlane_b32 s54, v241, 60
	v_readlane_b32 s70, v241, 46
	v_readlane_b32 s71, v241, 47
	v_readlane_b32 s72, v241, 48
	v_readlane_b32 s73, v241, 49
	v_readlane_b32 s74, v241, 50
	v_readlane_b32 s75, v241, 51
	v_readlane_b32 s82, v241, 58
	v_readlane_b32 s83, v241, 59
	v_readlane_b32 s55, v241, 61
	v_readlane_b32 s69, v241, 45
	v_readlane_b32 s76, v241, 52
	v_readlane_b32 s77, v241, 53
	v_readlane_b32 s78, v241, 54
	v_readlane_b32 s79, v241, 55
	v_readlane_b32 s80, v241, 56
	v_readlane_b32 s81, v241, 57
	s_waitcnt vmcnt(5)
	v_pk_mul_f32 v[2:3], v[2:3], v[18:19] op_sel_hi:[1,0]
	v_pk_mul_f32 v[4:5], v[4:5], v[18:19] op_sel_hi:[1,0]
	s_waitcnt vmcnt(3)
	v_pk_mul_f32 v[6:7], v[6:7], v[48:49] op_sel_hi:[1,0]
	v_pk_mul_f32 v[8:9], v[8:9], v[48:49] op_sel_hi:[1,0]
	ds_write2_b32 v37, v2, v3 offset1:1
	ds_write2_b32 v37, v4, v5 offset0:2 offset1:3
	ds_write2_b32 v38, v6, v7 offset1:1
	ds_write2_b32 v39, v8, v9 offset1:1
	s_waitcnt vmcnt(2)
	v_pk_mul_f32 v[2:3], v[10:11], v[50:51] op_sel_hi:[1,0]
	v_pk_mul_f32 v[4:5], v[12:13], v[50:51] op_sel_hi:[1,0]
	ds_write2_b32 v40, v2, v3 offset1:1
	ds_write2_b32 v41, v4, v5 offset1:1
	s_waitcnt vmcnt(0)
	v_pk_mul_f32 v[2:3], v[14:15], v[22:23] op_sel_hi:[1,0]
	v_pk_mul_f32 v[4:5], v[16:17], v[22:23] op_sel_hi:[1,0]
	ds_write2_b32 v42, v2, v3 offset1:1
	ds_write2_b32 v43, v4, v5 offset1:1
	s_waitcnt lgkmcnt(0)
	s_barrier
	ds_read2_b32 v[100:101], v27 offset1:65
	ds_read2_b32 v[102:103], v27 offset0:130 offset1:195
	ds_read2_b32 v[104:105], v44 offset0:4 offset1:69
	ds_read2_b32 v[106:107], v44 offset0:134 offset1:199
	ds_read2_b32 v[108:109], v29 offset1:65
	ds_read2_b32 v[110:111], v29 offset0:130 offset1:195
	ds_read2_b32 v[112:113], v45 offset0:4 offset1:69
	ds_read2_b32 v[114:115], v45 offset0:134 offset1:199
	s_waitcnt lgkmcnt(7)
	v_cvt_pk_bf16_f32 v2, v100, v101
	v_or_b32_e32 v8, s4, v25
	s_waitcnt lgkmcnt(6)
	v_cvt_pk_bf16_f32 v3, v102, v103
	v_lshl_or_b32 v8, v8, 11, v26
	s_waitcnt lgkmcnt(5)
	v_cvt_pk_bf16_f32 v4, v104, v105
	s_waitcnt lgkmcnt(4)
	v_cvt_pk_bf16_f32 v5, v106, v107
	v_add_lshl_u32 v8, v8, s5, 1
	global_store_dwordx4 v8, v[2:5], s[52:53]
	s_waitcnt lgkmcnt(3)
	s_nop 0
	v_cvt_pk_bf16_f32 v2, v108, v109
	s_waitcnt lgkmcnt(2)
	v_cvt_pk_bf16_f32 v3, v110, v111
	s_waitcnt lgkmcnt(1)
	v_cvt_pk_bf16_f32 v4, v112, v113
	v_add_u32_e32 v5, s4, v28
	v_lshl_or_b32 v5, v5, 11, v26
	v_add_lshl_u32 v8, v5, s5, 1
	s_waitcnt lgkmcnt(0)
	v_cvt_pk_bf16_f32 v5, v114, v115
	global_store_dwordx4 v8, v[2:5], s[52:53]
	s_barrier

; __device__ __forceinline__ unsigned cvt_pk(float lo, float hi) { unsigned r; asm volatile("v_cvt_pk_bf16_f32 %0, %1, %2" : "=v"(r) : "v"(lo), "v"(hi)); return r; }
; __device__ __forceinline__ int sigma64(int p) { return (p >> 5) * 16 + (p & 15) + 32 * ((p >> 4) & 1); }
; template <int WID>
; __device__ __forceinline__ void transpose_tile(const Params& p, bf16_t* Wt, int K, int ldw, const float* W, int nt_, int kt_, LAS float* scr, int tid) {
;     ...
;     {
;         const int c4 = (tid & 15) * 4; const int np = n0 + c4; int sc;
;         if (WID == 0) { sc = np < 1792 ? np : (np < 1856 ? 1792 + sigma64(np - 1792) : -1); }
;         else if (WID == 2) { const int h = np / 192, d = np - h * 192; sc = d < 128 ? np : h * 192 + 128 + sigma64(d - 128); }
;         else if (WID == 5) { const int i32 = np & 31; const int jj = (np & 96) + 8 * ((i32 >> 2) & 3) + 4 * (i32 >> 4) + (i32 & 3); sc = ((np >> 7) & 1) * DFF + (np >> 8) * 128 + jj; }
;         else sc = np;
;         f32x4 v[4];
; #pragma unroll
;         for (int i = 0; i < 4; ++i) { const int kk = (tid >> 4) + 32 * i; v[i] = sc >= 0 ? __builtin_nontemporal_load((const f32x4*)(W + (size_t)(k0 + kk) * ldw + sc)) : (f32x4){0.f, 0.f, 0.f, 0.f}; }
; #pragma unroll
;         for (int i = 0; i < 4; ++i) {
;             const int kk = (tid >> 4) + 32 * i; const int k = k0 + kk; float ksc = 1.0f;
;             if (WID == 2) ksc = p.in[14][k];
;             if (WID == 3) ksc = p.in[16][k];
;             if (WID == 4) ksc = (k < 1024 ? p.in[18][k] : p.in[19][k - 1024]);
;             if (WID == 5) ksc = p.in[21][k];
; #pragma unroll
;             for (int e = 0; e < 4; ++e) scr[kk * 65 + c4 + e] = v[i][e] * ksc;
;         }
;     }
;     __syncthreads();
; #pragma unroll
;     for (int j = 0; j < 2; ++j) {
;         const int idx = tid + 512 * j; const int r = idx >> 4, kg = (idx & 15) * 8; u32x4 w;
;         w.x = cvt_pk(scr[(kg + 0) * 65 + r], scr[(kg + 1) * 65 + r]); w.y = cvt_pk(scr[(kg + 2) * 65 + r], scr[(kg + 3) * 65 + r]);
;         w.z = cvt_pk(scr[(kg + 4) * 65 + r], scr[(kg + 5) * 65 + r]); w.w = cvt_pk(scr[(kg + 6) * 65 + r], scr[(kg + 7) * 65 + r]);
;         *(u32x4*)(Wt + ((size_t)(n0 + r) * K + k0 + kg)) = w;
;     }
;     __syncthreads();
.LBB0_78:
	s_andn2_b64 vcc, exec, s[0:1]
	s_cbranch_vccnz .LBB0_80
	s_and_b32 s0, s6, 0x7c0
	s_and_b32 s1, s9, 0xf80
	s_addk_i32 s1, 0xf480
	v_or_b32_e32 v2, s0, v1
	v_readlane_b32 s68, v241, 24
	v_or_b32_e32 v10, s1, v25
	v_lshlrev_b32_e32 v18, 2, v2
	v_readlane_b32 s70, v241, 26
	v_readlane_b32 s71, v241, 27
	v_readlane_b32 s69, v241, 25
	v_mov_b32_e32 v11, v19
	v_lshl_add_u64 v[2:3], s[70:71], 0, v[18:19]
	v_lshlrev_b32_e32 v18, 11, v10
	v_lshl_add_u64 v[14:15], v[18:19], 2, v[2:3]
	v_add_co_u32_e32 v6, vcc, 0x40000, v14
	v_lshl_add_u64 v[16:17], v[10:11], 2, s[68:69]
	s_nop 0
	v_addc_co_u32_e32 v7, vcc, 0, v15, vcc
	v_add_co_u32_e32 v12, vcc, 0x80000, v14
	global_load_dwordx4 v[2:5], v[14:15], off nt
	s_nop 0
	global_load_dwordx4 v[6:9], v[6:7], off nt
	v_addc_co_u32_e32 v13, vcc, 0, v15, vcc
	global_load_dword v18, v[16:17], off
	s_nop 0
	global_load_dwordx4 v[10:13], v[12:13], off nt
	s_nop 0
	global_load_dword v22, v[16:17], off offset:128
	v_add_co_u32_e32 v14, vcc, 0xc0000, v14
	global_load_dword v48, v[16:17], off offset:256
	s_nop 0
	v_addc_co_u32_e32 v15, vcc, 0, v15, vcc
	global_load_dword v50, v[16:17], off offset:384
	s_nop 0
	global_load_dwordx4 v[14:17], v[14:15], off nt
	v_readlane_b32 s4, v241, 40
	v_readlane_b32 s5, v241, 41
	v_readlane_b32 s72, v241, 28
	v_readlane_b32 s73, v241, 29
	v_readlane_b32 s74, v241, 30
	v_readlane_b32 s75, v241, 31
	v_readlane_b32 s76, v241, 32
	v_readlane_b32 s77, v241, 33
	v_readlane_b32 s78, v241, 34
	v_readlane_b32 s79, v241, 35
	v_readlane_b32 s80, v241, 36
	v_readlane_b32 s81, v241, 37
	v_readlane_b32 s82, v241, 38
	v_readlane_b32 s83, v241, 39
	v_readlane_b32 s68, v241, 44
	v_readlane_b32 s54, v241, 60
	v_readlane_b32 s70, v241, 46
	v_readlane_b32 s71, v241, 47
	v_readlane_b32 s72, v241, 48
	v_readlane_b32 s73, v241, 49
	v_readlane_b32 s74, v241, 50
	v_readlane_b32 s75, v241, 51
	v_readlane_b32 s82, v241, 58
	v_readlane_b32 s83, v241, 59
	v_readlane_b32 s55, v241, 61
	v_readlane_b32 s69, v241, 45
	v_readlane_b32 s76, v241, 52
	v_readlane_b32 s77, v241, 53
	v_readlane_b32 s78, v241, 54
	v_readlane_b32 s79, v241, 55
	v_readlane_b32 s80, v241, 56
	v_readlane_b32 s81, v241, 57
	s_waitcnt vmcnt(5)
	v_pk_mul_f32 v[2:3], v[2:3], v[18:19] op_sel_hi:[1,0]
	v_pk_mul_f32 v[4:5], v[4:5], v[18:19] op_sel_hi:[1,0]
	ds_write2_b32 v37, v2, v3 offset1:1
	ds_write2_b32 v37, v4, v5 offset0:2 offset1:3
	s_waitcnt vmcnt(3)
	v_pk_mul_f32 v[2:3], v[6:7], v[22:23] op_sel_hi:[1,0]
	v_pk_mul_f32 v[4:5], v[8:9], v[22:23] op_sel_hi:[1,0]
	ds_write2_b32 v38, v2, v3 offset1:1
	ds_write2_b32 v39, v4, v5 offset1:1
	s_waitcnt vmcnt(2)
	v_pk_mul_f32 v[2:3], v[10:11], v[48:49] op_sel_hi:[1,0]
	v_pk_mul_f32 v[4:5], v[12:13], v[48:49] op_sel_hi:[1,0]
	ds_write2_b32 v40, v2, v3 offset1:1
	ds_write2_b32 v41, v4, v5 offset1:1
	s_waitcnt vmcnt(0)
	v_pk_mul_f32 v[2:3], v[14:15], v[50:51] op_sel_hi:[1,0]
	v_pk_mul_f32 v[4:5], v[16:17], v[50:51] op_sel_hi:[1,0]
	ds_write2_b32 v42, v2, v3 offset1:1
	ds_write2_b32 v43, v4, v5 offset1:1
	s_waitcnt lgkmcnt(0)
	s_barrier
	ds_read2_b32 v[100:101], v27 offset1:65
	ds_read2_b32 v[102:103], v27 offset0:130 offset1:195
	ds_read2_b32 v[104:105], v44 offset0:4 offset1:69
	ds_read2_b32 v[106:107], v44 offset0:134 offset1:199
	ds_read2_b32 v[108:109], v29 offset1:65
	ds_read2_b32 v[110:111], v29 offset0:130 offset1:195
	ds_read2_b32 v[112:113], v45 offset0:4 offset1:69
	ds_read2_b32 v[114:115], v45 offset0:134 offset1:199
	v_or_b32_e32 v8, s0, v25
	s_waitcnt lgkmcnt(7)
	v_cvt_pk_bf16_f32 v2, v100, v101
	v_lshl_or_b32 v8, v8, 8, v26
	s_waitcnt lgkmcnt(6)
	v_cvt_pk_bf16_f32 v3, v102, v103
	v_add_u32_e32 v18, s1, v8
	s_waitcnt lgkmcnt(5)
	v_cvt_pk_bf16_f32 v4, v104, v105
	s_waitcnt lgkmcnt(4)
	v_cvt_pk_bf16_f32 v5, v106, v107
	v_lshl_add_u64 v[8:9], v[18:19], 1, s[4:5]
	global_store_dwordx4 v[8:9], v[2:5], off
	s_waitcnt lgkmcnt(3)
	s_nop 0
	v_cvt_pk_bf16_f32 v2, v108, v109
	s_waitcnt lgkmcnt(2)
	v_cvt_pk_bf16_f32 v3, v110, v111
	s_waitcnt lgkmcnt(1)
	v_cvt_pk_bf16_f32 v4, v112, v113
	v_add_u32_e32 v5, s0, v28
	v_lshl_or_b32 v5, v5, 8, v26
	v_add_u32_e32 v18, s1, v5
	v_lshl_add_u64 v[8:9], v[18:19], 1, s[4:5]
	s_waitcnt lgkmcnt(0)
	v_cvt_pk_bf16_f32 v5, v114, v115
	global_store_dwordx4 v[8:9], v[2:5], off
	s_barrier

; __device__ __forceinline__ unsigned cvt_pk(float lo, float hi) { unsigned r; asm volatile("v_cvt_pk_bf16_f32 %0, %1, %2" : "=v"(r) : "v"(lo), "v"(hi)); return r; }
; __device__ __forceinline__ int sigma64(int p) { return (p >> 5) * 16 + (p & 15) + 32 * ((p >> 4) & 1); }
; template <int WID>
; __device__ __forceinline__ void transpose_tile(const Params& p, bf16_t* Wt, int K, int ldw, const float* W, int nt_, int kt_, LAS float* scr, int tid) {
;     ...
;     {
;         const int c4 = (tid & 15) * 4; const int np = n0 + c4; int sc;
;         if (WID == 0) { sc = np < 1792 ? np : (np < 1856 ? 1792 + sigma64(np - 1792) : -1); }
;         else if (WID == 2) { const int h = np / 192, d = np - h * 192; sc = d < 128 ? np : h * 192 + 128 + sigma64(d - 128); }
;         else if (WID == 5) { const int i32 = np & 31; const int jj = (np & 96) + 8 * ((i32 >> 2) & 3) + 4 * (i32 >> 4) + (i32 & 3); sc = ((np >> 7) & 1) * DFF + (np >> 8) * 128 + jj; }
;         else sc = np;
;         f32x4 v[4];
; #pragma unroll
;         for (int i = 0; i < 4; ++i) { const int kk = (tid >> 4) + 32 * i; v[i] = sc >= 0 ? __builtin_nontemporal_load((const f32x4*)(W + (size_t)(k0 + kk) * ldw + sc)) : (f32x4){0.f, 0.f, 0.f, 0.f}; }
; #pragma unroll
;         for (int i = 0; i < 4; ++i) {
;             const int kk = (tid >> 4) + 32 * i; const int k = k0 + kk; float ksc = 1.0f;
;             if (WID == 2) ksc = p.in[14][k];
;             if (WID == 3) ksc = p.in[16][k];
;             if (WID == 4) ksc = (k < 1024 ? p.in[18][k] : p.in[19][k - 1024]);
;             if (WID == 5) ksc = p.in[21][k];
; #pragma unroll
;             for (int e = 0; e < 4; ++e) scr[kk * 65 + c4 + e] = v[i][e] * ksc;
;         }
;     }
;     __syncthreads();
; #pragma unroll
;     for (int j = 0; j < 2; ++j) {
;         const int idx = tid + 512 * j; const int r = idx >> 4, kg = (idx & 15) * 8; u32x4 w;
;         w.x = cvt_pk(scr[(kg + 0) * 65 + r], scr[(kg + 1) * 65 + r]); w.y = cvt_pk(scr[(kg + 2) * 65 + r], scr[(kg + 3) * 65 + r]);
;         w.z = cvt_pk(scr[(kg + 4) * 65 + r], scr[(kg + 5) * 65 + r]); w.w = cvt_pk(scr[(kg + 6) * 65 + r], scr[(kg + 7) * 65 + r]);
;         *(u32x4*)(Wt + ((size_t)(n0 + r) * K + k0 + kg)) = w;
;     }
;     __syncthreads();
.LBB0_81:
	s_andn2_b64 vcc, exec, s[0:1]
	s_cbranch_vccnz .LBB0_85
	s_xor_b32 s0, s45, 0xff80
	s_and_b32 s1, s0, 0xff
	s_mulk_i32 s1, 0xab
	s_bfe_u32 s5, s1, 0x4000c
	s_mul_i32 s1, s5, 24
	s_sub_i32 s0, s0, s1
	s_and_b32 s0, s0, 0xff
	s_lshl_b32 s4, s0, 6
	s_mulk_i32 s0, 0xab
	s_bfe_u32 s46, s0, 0x70009
	v_or_b32_e32 v2, s4, v1
	s_mulk_i32 s46, 0xc0
	v_subrev_u32_e32 v3, s46, v2
	v_cmp_lt_i32_e32 vcc, s36, v3
	s_and_saveexec_b64 s[0:1], vcc
	v_add_u32_e32 v2, 0xffffff80, v3
	v_lshrrev_b32_e32 v3, 1, v2
	v_lshlrev_b32_e32 v2, 1, v2
	v_and_b32_e32 v3, 0x3f0, v3
	v_and_b32_e32 v2, 32, v2
	v_add_u32_e32 v4, s46, v31
	v_add3_u32 v2, v4, v3, v2
	s_or_b64 exec, exec, s[0:1]
	s_and_b32 s0, 0xffff, s5
	s_lshl_b32 s0, s0, 7
	v_or_b32_e32 v11, s0, v25
	v_readlane_b32 s16, v241, 8
	v_lshlrev_b32_e32 v18, 2, v2
	v_readlane_b32 s30, v241, 22
	v_readlane_b32 s31, v241, 23
	v_mul_u32_u24_e32 v4, 0x600, v11
	v_readlane_b32 s28, v241, 20
	v_lshl_add_u64 v[2:3], s[30:31], 0, v[18:19]
	v_lshlrev_b32_e32 v18, 2, v4
	v_lshl_add_u64 v[14:15], v[2:3], 0, v[18:19]
	v_add_co_u32_e32 v6, vcc, 0x30000, v14
	v_readlane_b32 s29, v241, 21
	s_nop 0
	v_addc_co_u32_e32 v7, vcc, 0, v15, vcc
	v_add_co_u32_e32 v10, vcc, 0x60000, v14
	v_lshlrev_b32_e32 v16, 2, v11
	global_load_dwordx4 v[2:5], v[14:15], off nt
	s_nop 0
	global_load_dwordx4 v[6:9], v[6:7], off nt
	v_addc_co_u32_e32 v11, vcc, 0, v15, vcc
	global_load_dword v18, v16, s[28:29]
	s_nop 0
	global_load_dwordx4 v[10:13], v[10:11], off nt
	s_nop 0
	global_load_dword v22, v16, s[28:29] offset:128
	v_add_co_u32_e32 v14, vcc, 0x90000, v14
	global_load_dword v48, v16, s[28:29] offset:256
	s_nop 0
	v_addc_co_u32_e32 v15, vcc, 0, v15, vcc
	global_load_dword v50, v16, s[28:29] offset:384
	s_nop 0
	global_load_dwordx4 v[14:17], v[14:15], off nt
	v_readlane_b32 s17, v241, 9
	v_readlane_b32 s18, v241, 10
	v_readlane_b32 s19, v241, 11
	v_readlane_b32 s20, v241, 12
	v_readlane_b32 s21, v241, 13
	v_readlane_b32 s22, v241, 14
	v_readlane_b32 s23, v241, 15
	v_readlane_b32 s24, v241, 16
	v_readlane_b32 s25, v241, 17
	v_readlane_b32 s26, v241, 18
	v_readlane_b32 s27, v241, 19
	s_waitcnt vmcnt(5)
	v_pk_mul_f32 v[2:3], v[2:3], v[18:19] op_sel_hi:[1,0]
	v_pk_mul_f32 v[4:5], v[4:5], v[18:19] op_sel_hi:[1,0]
	ds_write2_b32 v37, v2, v3 offset1:1
	ds_write2_b32 v37, v4, v5 offset0:2 offset1:3
	s_waitcnt vmcnt(3)
	v_pk_mul_f32 v[2:3], v[6:7], v[22:23] op_sel_hi:[1,0]
	v_pk_mul_f32 v[4:5], v[8:9], v[22:23] op_sel_hi:[1,0]
	ds_write2_b32 v38, v2, v3 offset1:1
	ds_write2_b32 v39, v4, v5 offset1:1
	s_waitcnt vmcnt(2)
	v_pk_mul_f32 v[2:3], v[10:11], v[48:49] op_sel_hi:[1,0]
	v_pk_mul_f32 v[4:5], v[12:13], v[48:49] op_sel_hi:[1,0]
	ds_write2_b32 v40, v2, v3 offset1:1
	ds_write2_b32 v41, v4, v5 offset1:1
	s_waitcnt vmcnt(0)
	v_pk_mul_f32 v[2:3], v[14:15], v[50:51] op_sel_hi:[1,0]
	v_pk_mul_f32 v[4:5], v[16:17], v[50:51] op_sel_hi:[1,0]
	ds_write2_b32 v42, v2, v3 offset1:1
	ds_write2_b32 v43, v4, v5 offset1:1
	s_waitcnt lgkmcnt(0)
	s_barrier
	ds_read2_b32 v[100:101], v27 offset1:65
	ds_read2_b32 v[102:103], v27 offset0:130 offset1:195
	ds_read2_b32 v[104:105], v44 offset0:4 offset1:69
	ds_read2_b32 v[106:107], v44 offset0:134 offset1:199
	ds_read2_b32 v[108:109], v29 offset1:65
	ds_read2_b32 v[110:111], v29 offset0:130 offset1:195
	ds_read2_b32 v[112:113], v45 offset0:4 offset1:69
	ds_read2_b32 v[114:115], v45 offset0:134 offset1:199
	s_waitcnt lgkmcnt(7)
	v_cvt_pk_bf16_f32 v2, v100, v101
	v_or_b32_e32 v8, s4, v25
	s_waitcnt lgkmcnt(6)
	v_cvt_pk_bf16_f32 v3, v102, v103
	v_lshl_or_b32 v8, v8, 9, v26
	s_waitcnt lgkmcnt(5)
	v_cvt_pk_bf16_f32 v4, v104, v105
	s_waitcnt lgkmcnt(4)
	v_cvt_pk_bf16_f32 v5, v106, v107
	v_add_lshl_u32 v8, v8, s0, 1
	global_store_dwordx4 v8, v[2:5], s[34:35]
	s_waitcnt lgkmcnt(3)
	s_nop 0
	v_cvt_pk_bf16_f32 v2, v108, v109
	s_waitcnt lgkmcnt(2)
	v_cvt_pk_bf16_f32 v3, v110, v111
	s_waitcnt lgkmcnt(1)
	v_cvt_pk_bf16_f32 v4, v112, v113
	v_add_u32_e32 v5, s4, v28
	v_lshl_or_b32 v5, v5, 9, v26
	v_add_lshl_u32 v8, v5, s0, 1
	s_waitcnt lgkmcnt(0)
	v_cvt_pk_bf16_f32 v5, v114, v115
	global_store_dwordx4 v8, v[2:5], s[34:35]
	s_barrier

; __device__ __forceinline__ unsigned cvt_pk(float lo, float hi) { unsigned r; asm volatile("v_cvt_pk_bf16_f32 %0, %1, %2" : "=v"(r) : "v"(lo), "v"(hi)); return r; }
; __device__ __forceinline__ int sigma64(int p) { return (p >> 5) * 16 + (p & 15) + 32 * ((p >> 4) & 1); }
; template <int WID>
; __device__ __forceinline__ void transpose_tile(const Params& p, bf16_t* Wt, int K, int ldw, const float* W, int nt_, int kt_, LAS float* scr, int tid) {
;     ...
;     {
;         const int c4 = (tid & 15) * 4; const int np = n0 + c4; int sc;
;         if (WID == 0) { sc = np < 1792 ? np : (np < 1856 ? 1792 + sigma64(np - 1792) : -1); }
;         else if (WID == 2) { const int h = np / 192, d = np - h * 192; sc = d < 128 ? np : h * 192 + 128 + sigma64(d - 128); }
;         else if (WID == 5) { const int i32 = np & 31; const int jj = (np & 96) + 8 * ((i32 >> 2) & 3) + 4 * (i32 >> 4) + (i32 & 3); sc = ((np >> 7) & 1) * DFF + (np >> 8) * 128 + jj; }
;         else sc = np;
;         f32x4 v[4];
; #pragma unroll
;         for (int i = 0; i < 4; ++i) { const int kk = (tid >> 4) + 32 * i; v[i] = sc >= 0 ? __builtin_nontemporal_load((const f32x4*)(W + (size_t)(k0 + kk) * ldw + sc)) : (f32x4){0.f, 0.f, 0.f, 0.f}; }
; #pragma unroll
;         for (int i = 0; i < 4; ++i) {
;             const int kk = (tid >> 4) + 32 * i; const int k = k0 + kk; float ksc = 1.0f;
;             if (WID == 2) ksc = p.in[14][k];
;             if (WID == 3) ksc = p.in[16][k];
;             if (WID == 4) ksc = (k < 1024 ? p.in[18][k] : p.in[19][k - 1024]);
;             if (WID == 5) ksc = p.in[21][k];
; #pragma unroll
;             for (int e = 0; e < 4; ++e) scr[kk * 65 + c4 + e] = v[i][e] * ksc;
;         }
;     }
;     __syncthreads();
; #pragma unroll
;     for (int j = 0; j < 2; ++j) {
;         const int idx = tid + 512 * j; const int r = idx >> 4, kg = (idx & 15) * 8; u32x4 w;
;         w.x = cvt_pk(scr[(kg + 0) * 65 + r], scr[(kg + 1) * 65 + r]); w.y = cvt_pk(scr[(kg + 2) * 65 + r], scr[(kg + 3) * 65 + r]);
;         w.z = cvt_pk(scr[(kg + 4) * 65 + r], scr[(kg + 5) * 65 + r]); w.w = cvt_pk(scr[(kg + 6) * 65 + r], scr[(kg + 7) * 65 + r]);
;         *(u32x4*)(Wt + ((size_t)(n0 + r) * K + k0 + kg)) = w;
;     }
;     __syncthreads();
.LBB0_86:
	s_andn2_b64 vcc, exec, s[0:1]
	s_cbranch_vccnz .LBB0_88
	s_and_b32 s0, s6, 0x3c0
	s_and_b32 s1, s44, 0x1f80
	s_addk_i32 s1, 0xf000
	v_or_b32_e32 v2, s0, v1
	v_readlane_b32 s16, v241, 8
	v_or_b32_e32 v4, s1, v25
	v_lshlrev_b32_e32 v18, 2, v2
	v_readlane_b32 s24, v241, 16
	v_readlane_b32 s25, v241, 17
	s_mov_b32 s4, 0x40000
	v_readlane_b32 s17, v241, 9
	v_lshl_add_u64 v[2:3], s[24:25], 0, v[18:19]
	v_lshlrev_b32_e32 v18, 10, v4
	v_lshl_add_u64 v[14:15], v[18:19], 2, v[2:3]
	v_add_co_u32_e32 v6, vcc, 0x20000, v14
	v_readlane_b32 s18, v241, 10
	s_nop 0
	v_addc_co_u32_e32 v7, vcc, 0, v15, vcc
	global_load_dwordx4 v[2:5], v[14:15], off nt
	s_nop 0
	global_load_dwordx4 v[6:9], v[6:7], off nt
	v_add_co_u32_e32 v10, vcc, s4, v14
	v_readlane_b32 s19, v241, 11
	s_nop 0
	v_addc_co_u32_e32 v11, vcc, 0, v15, vcc
	global_load_dwordx4 v[10:13], v[10:11], off nt
	v_add_co_u32_e32 v14, vcc, s37, v14
	v_readlane_b32 s20, v241, 12
	s_nop 0
	v_addc_co_u32_e32 v15, vcc, 0, v15, vcc
	global_load_dwordx4 v[14:17], v[14:15], off nt
	v_readlane_b32 s21, v241, 13
	v_readlane_b32 s22, v241, 14
	v_readlane_b32 s23, v241, 15
	v_readlane_b32 s26, v241, 18
	v_readlane_b32 s27, v241, 19
	v_readlane_b32 s28, v241, 20
	v_readlane_b32 s29, v241, 21
	v_readlane_b32 s30, v241, 22
	v_readlane_b32 s31, v241, 23
	s_waitcnt vmcnt(3)
	ds_write2_b32 v37, v2, v3 offset1:1
	ds_write2_b32 v37, v4, v5 offset0:2 offset1:3
	s_waitcnt vmcnt(2)
	ds_write2_b32 v38, v6, v7 offset1:1
	ds_write2_b32 v39, v8, v9 offset1:1
	s_waitcnt vmcnt(1)
	ds_write2_b32 v40, v10, v11 offset1:1
	ds_write2_b32 v41, v12, v13 offset1:1
	s_waitcnt vmcnt(0)
	ds_write2_b32 v42, v14, v15 offset1:1
	ds_write2_b32 v43, v16, v17 offset1:1
	s_waitcnt lgkmcnt(0)
	s_barrier
	ds_read2_b32 v[100:101], v27 offset1:65
	ds_read2_b32 v[102:103], v27 offset0:130 offset1:195
	ds_read2_b32 v[104:105], v44 offset0:4 offset1:69
	ds_read2_b32 v[106:107], v44 offset0:134 offset1:199
	ds_read2_b32 v[108:109], v29 offset1:65
	ds_read2_b32 v[110:111], v29 offset0:130 offset1:195
	ds_read2_b32 v[112:113], v45 offset0:4 offset1:69
	ds_read2_b32 v[114:115], v45 offset0:134 offset1:199
	v_or_b32_e32 v8, s0, v25
	s_waitcnt lgkmcnt(7)
	v_cvt_pk_bf16_f32 v2, v100, v101
	v_lshl_or_b32 v8, v8, 10, v26
	s_waitcnt lgkmcnt(6)
	v_cvt_pk_bf16_f32 v3, v102, v103
	v_add_u32_e32 v18, s1, v8
	s_waitcnt lgkmcnt(5)
	v_cvt_pk_bf16_f32 v4, v104, v105
	s_waitcnt lgkmcnt(4)
	v_cvt_pk_bf16_f32 v5, v106, v107
	v_lshl_add_u64 v[8:9], v[18:19], 1, s[54:55]
	global_store_dwordx4 v[8:9], v[2:5], off
	s_waitcnt lgkmcnt(3)
	s_nop 0
	v_cvt_pk_bf16_f32 v2, v108, v109
	s_waitcnt lgkmcnt(2)
	v_cvt_pk_bf16_f32 v3, v110, v111
	s_waitcnt lgkmcnt(1)
	v_cvt_pk_bf16_f32 v4, v112, v113
	v_add_u32_e32 v5, s0, v28
	v_lshl_or_b32 v5, v5, 10, v26
	v_add_u32_e32 v18, s1, v5
	v_lshl_add_u64 v[8:9], v[18:19], 1, s[54:55]
	s_waitcnt lgkmcnt(0)
	v_cvt_pk_bf16_f32 v5, v114, v115
	global_store_dwordx4 v[8:9], v[2:5], off
	s_barrier
